# counter wait loops (panel counters, sample/scan counters): poll back-off s_sleep 8 -> s_sleep 1 (timing only)
# speedup vs baseline: 1.0068x; 1.0068x over previous
.LBB0_806:
	global_load_dword v4, v1, s[6:7] sc1
	s_mov_b64 s[18:19], -1
	s_waitcnt vmcnt(0)
	v_cmp_lt_u32_e32 vcc, 21, v4
	s_cbranch_vccnz .LBB0_805
	s_sleep 1
	s_memrealtime s[18:19]
	s_waitcnt lgkmcnt(0)
	s_sub_u32 s18, s18, s10
	s_subb_u32 s19, s19, s11
	v_cmp_gt_u64_e64 s[18:19], s[18:19], v[2:3]
	s_branch .LBB0_805

.LBB0_837:
	global_load_dword v4, v1, s[8:9] sc1
	s_mov_b64 s[18:19], -1
	s_waitcnt vmcnt(0)
	v_cmp_lt_u32_e32 vcc, 3, v4
	s_cbranch_vccnz .LBB0_836
	s_sleep 1
	s_memrealtime s[18:19]
	s_waitcnt lgkmcnt(0)
	s_sub_u32 s18, s18, s10
	s_subb_u32 s19, s19, s11
	v_cmp_gt_u64_e64 s[18:19], s[18:19], v[2:3]
	s_branch .LBB0_836

.LBB0_871:
	global_load_dword v4, v1, s[10:11] sc1
	s_mov_b64 s[12:13], -1
	s_waitcnt vmcnt(0)
	v_cmp_lt_u32_e32 vcc, 3, v4
	s_cbranch_vccnz .LBB0_870
	s_sleep 1
	s_memrealtime s[4:5]
	s_waitcnt lgkmcnt(0)
	s_sub_u32 s4, s4, s8
	s_subb_u32 s5, s5, s9
	v_cmp_gt_u64_e64 s[12:13], s[4:5], v[2:3]
	s_branch .LBB0_870

.LBB0_999:
	global_load_dword v4, v1, s[8:9] sc1
	s_mov_b64 s[12:13], -1
	s_waitcnt vmcnt(0)
	v_cmp_lt_u32_e32 vcc, 3, v4
	s_cbranch_vccnz .LBB0_998
	s_sleep 1
	s_memrealtime s[12:13]
	s_waitcnt lgkmcnt(0)
	s_sub_u32 s12, s12, s6
	s_subb_u32 s13, s13, s7
	v_cmp_gt_u64_e64 s[12:13], s[12:13], v[2:3]
	s_branch .LBB0_998

.LBB0_2902:
	s_nop 3
	global_load_dword v4, v1, s[12:13] sc1
	s_mov_b64 s[10:11], -1
	s_waitcnt vmcnt(0)
	v_cmp_lt_u32_e32 vcc, s2, v4
	s_cbranch_vccnz .LBB0_2901
	s_sleep 1
	s_memrealtime s[10:11]
	s_waitcnt lgkmcnt(0)
	s_sub_u32 s10, s10, s8
	s_subb_u32 s11, s11, s9
	v_cmp_gt_u64_e64 s[10:11], s[10:11], v[2:3]
	s_branch .LBB0_2901

.LBB0_2932:
	global_load_dword v4, v1, s[8:9] sc1
	s_mov_b64 s[12:13], -1
	s_waitcnt vmcnt(0)
	v_cmp_lt_u32_e32 vcc, 3, v4
	s_cbranch_vccnz .LBB0_2931
	s_sleep 1
	s_memrealtime s[2:3]
	s_waitcnt lgkmcnt(0)
	s_sub_u32 s2, s2, s10
	s_subb_u32 s3, s3, s11
	v_cmp_gt_u64_e64 s[12:13], s[2:3], v[2:3]
	s_branch .LBB0_2931

.LBB0_2941:
	v_readlane_b32 s10, v228, 17
	v_readlane_b32 s11, v228, 18
	s_nop 4
	global_load_dword v4, v1, s[10:11] sc1
	s_mov_b64 s[10:11], -1
	s_waitcnt vmcnt(0)
	v_cmp_lt_u32_e32 vcc, s2, v4
	s_cbranch_vccnz .LBB0_2940
	s_sleep 1
	s_memrealtime s[10:11]
	s_waitcnt lgkmcnt(0)
	s_sub_u32 s10, s10, s8
	s_subb_u32 s11, s11, s9
	v_cmp_gt_u64_e64 s[10:11], s[10:11], v[2:3]
	s_branch .LBB0_2940

.LBB0_3159:
	global_load_dword v4, v1, s[6:7] sc1
	s_mov_b64 s[24:25], -1
	s_waitcnt vmcnt(0)
	v_cmp_lt_u32_e32 vcc, 21, v4
	s_cbranch_vccnz .LBB0_3158
	s_sleep 1
	s_memrealtime s[24:25]
	s_waitcnt lgkmcnt(0)
	s_sub_u32 s24, s24, s10
	s_subb_u32 s25, s25, s11
	v_cmp_gt_u64_e64 s[24:25], s[24:25], v[2:3]
	s_branch .LBB0_3158

.LBB0_3189:
	global_load_dword v4, v1, s[8:9] sc1
	s_mov_b64 s[24:25], -1
	s_waitcnt vmcnt(0)
	v_cmp_lt_u32_e32 vcc, 3, v4
	s_cbranch_vccnz .LBB0_3188
	s_sleep 1
	s_memrealtime s[24:25]
	s_waitcnt lgkmcnt(0)
	s_sub_u32 s24, s24, s10
	s_subb_u32 s25, s25, s11
	v_cmp_gt_u64_e64 s[24:25], s[24:25], v[2:3]
	s_branch .LBB0_3188

.LBB0_3336:
	global_load_dword v4, v1, s[8:9] sc1
	s_mov_b64 s[16:17], -1
	s_waitcnt vmcnt(0)
	v_cmp_lt_u32_e32 vcc, 3, v4
	s_cbranch_vccnz .LBB0_3335
	s_sleep 1
	s_memrealtime s[16:17]
	s_waitcnt lgkmcnt(0)
	s_sub_u32 s16, s16, s6
	s_subb_u32 s17, s17, s7
	v_cmp_gt_u64_e64 s[16:17], s[16:17], v[2:3]
	s_branch .LBB0_3335

.LBB0_3413:
	global_load_dword v4, v1, s[6:7] sc1
	s_mov_b64 s[20:21], -1
	s_waitcnt vmcnt(0)
	v_cmp_lt_u32_e32 vcc, 21, v4
	s_cbranch_vccnz .LBB0_3412
	s_sleep 1
	s_memrealtime s[20:21]
	s_waitcnt lgkmcnt(0)
	s_sub_u32 s20, s20, s10
	s_subb_u32 s21, s21, s11
	v_cmp_gt_u64_e64 s[20:21], s[20:21], v[2:3]
	s_branch .LBB0_3412

.LBB0_3444:
	global_load_dword v4, v1, s[8:9] sc1
	s_mov_b64 s[20:21], -1
	s_waitcnt vmcnt(0)
	v_cmp_lt_u32_e32 vcc, 3, v4
	s_cbranch_vccnz .LBB0_3443
	s_sleep 1
	s_memrealtime s[20:21]
	s_waitcnt lgkmcnt(0)
	s_sub_u32 s20, s20, s10
	s_subb_u32 s21, s21, s11
	v_cmp_gt_u64_e64 s[20:21], s[20:21], v[2:3]
	s_branch .LBB0_3443

.LBB0_5548:
	v_readlane_b32 s10, v228, 29
	v_readlane_b32 s11, v228, 30
	s_nop 4
	global_load_dword v4, v1, s[10:11] sc1
	s_mov_b64 s[10:11], -1
	s_waitcnt vmcnt(0)
	v_cmp_lt_u32_e32 vcc, s2, v4
	s_cbranch_vccnz .LBB0_5547
	s_sleep 1
	s_memrealtime s[10:11]
	s_waitcnt lgkmcnt(0)
	s_sub_u32 s10, s10, s8
	s_subb_u32 s11, s11, s9
	v_cmp_gt_u64_e64 s[10:11], s[10:11], v[2:3]
	s_branch .LBB0_5547

.LBB0_5766:
	global_load_dword v4, v1, s[6:7] sc1
	s_mov_b64 s[12:13], -1
	s_waitcnt vmcnt(0)
	v_cmp_lt_u32_e32 vcc, 21, v4
	s_cbranch_vccnz .LBB0_5765
	s_sleep 1
	s_memrealtime s[12:13]
	s_waitcnt lgkmcnt(0)
	s_sub_u32 s12, s12, s10
	s_subb_u32 s13, s13, s11
	v_cmp_gt_u64_e64 s[12:13], s[12:13], v[2:3]
	s_branch .LBB0_5765

.LBB0_5796:
	global_load_dword v4, v1, s[8:9] sc1
	s_mov_b64 s[12:13], -1
	s_waitcnt vmcnt(0)
	v_cmp_lt_u32_e32 vcc, 3, v4
	s_cbranch_vccnz .LBB0_5795
	s_sleep 1
	s_memrealtime s[12:13]
	s_waitcnt lgkmcnt(0)
	s_sub_u32 s12, s12, s10
	s_subb_u32 s13, s13, s11
	v_cmp_gt_u64_e64 s[12:13], s[12:13], v[2:3]
	s_branch .LBB0_5795

.LBB0_5943:
	global_load_dword v4, v1, s[8:9] sc1
	s_mov_b64 s[4:5], -1
	s_waitcnt vmcnt(0)
	v_cmp_lt_u32_e32 vcc, 3, v4
	s_cbranch_vccnz .LBB0_5942
	s_sleep 1
	s_memrealtime s[4:5]
	s_waitcnt lgkmcnt(0)
	s_sub_u32 s4, s4, s2
	s_subb_u32 s5, s5, s3
	v_cmp_gt_u64_e64 s[4:5], s[4:5], v[2:3]
	s_branch .LBB0_5942
